# stagger variant I: 4-group stagger at in-proj phases, 2-group 3.5us stagger at out-proj phases and attention
# baseline (speedup 1.0000x reference)
;   DI bf16_t* wt_out0() const { return (bf16_t*)(ws + OFF_WT_OUT0); }
;   DI bf16_t* h() const { return (bf16_t*)(ws + OFF_H); }
; DI void phase_gemm_out(const Params& p, char* smem, const bf16_t* Wt, const float* R, float* O) {
;   u32x4 ra[4], rb[4]; bool pre = false;
;   for (int t = blockIdx.x; t < 64 * 8; t += gridDim.x) {
;     const int mt = t & 63, nt = t >> 6, tn = t + gridDim.x;
;     const bool has_next = tn < 64 * 8;
;     const GTile tl{p.h(), D, Wt, D, D, mt * 256, nt * 256}, nx{p.h(), D, Wt, D, D, (tn & 63) * 256, (tn >> 6) * 256};
; template <int PH>
; DI void run_phase(const Params& p, char* smem) {
;     ...
;   else if (PH == 6) phase_gemm_out(p, smem, p.wt_out0(), p.x, p.out);
.LBB0_742:
	s_or_b64 exec, exec, s[0:1]
	s_bitcmp1_b32 s84, 3
	s_cbranch_scc0 .Lstag_6_0
	s_sleep 127
.Lstag_6_0:
	v_cndmask_b32_e64 v0, 0, 1, s[6:7]
	v_cmp_ne_u32_e64 s[74:75], 1, v0
	s_andn2_b64 vcc, exec, s[6:7]
	s_waitcnt lgkmcnt(0)
	s_barrier
	s_cbranch_vccnz .LBB0_767
	s_add_u32 s16, s22, 0x1100000
	s_addc_u32 s17, s23, 0
	s_add_u32 s18, s22, 0x40c0000
	s_addc_u32 s19, s23, 0
	s_add_i32 s0, s84, s96
	s_lshl_b32 s24, s84, 2
	s_lshl_b32 s25, s96, 2
	s_lshl_b32 s26, s84, 8
	s_lshl_b32 s27, s96, 8
	s_lshl_b32 s28, s0, 19
	s_lshl_b32 s29, s96, 19
	s_mov_b64 s[12:13], 0
	v_mov_b32_e32 v185, 0
	s_mov_b32 s30, 0x40000
	s_mov_b32 s31, 0x80000
	s_mov_b32 s34, 0xc0000
	s_movk_i32 s35, 0x90
	s_mov_b64 s[0:1], 0x40000
	s_mov_b64 s[8:9], 0x80000
	s_add_i32 s36, 16, 0x12000
	s_add_i32 s37, 16, 0x1b000
	s_mov_b32 s38, s84
	s_branch .LBB0_745

;   DI bf16_t* wt_out1() const { return (bf16_t*)(ws + OFF_WT_OUT1); }
;   DI bf16_t* h() const { return (bf16_t*)(ws + OFF_H); }
; DI void phase_gemm_out(const Params& p, char* smem, const bf16_t* Wt, const float* R, float* O) {
;   u32x4 ra[4], rb[4]; bool pre = false;
;   for (int t = blockIdx.x; t < 64 * 8; t += gridDim.x) {
;     const int mt = t & 63, nt = t >> 6, tn = t + gridDim.x;
;     const bool has_next = tn < 64 * 8;
;     const GTile tl{p.h(), D, Wt, D, D, mt * 256, nt * 256}, nx{p.h(), D, Wt, D, D, (tn & 63) * 256, (tn >> 6) * 256};
; template <int PH>
; DI void run_phase(const Params& p, char* smem) {
;     ...
;   else if (PH == 11) phase_gemm_out(p, smem, p.wt_out1(), p.out, p.out);
.LBB0_1630:
	s_or_b64 exec, exec, s[0:1]
	s_bitcmp1_b32 s84, 3
	s_cbranch_scc0 .Lstag_11_0
	s_sleep 127
.Lstag_11_0:
	s_and_b64 vcc, exec, s[74:75]
	s_waitcnt lgkmcnt(0)
	s_barrier
	s_cbranch_vccnz .LBB0_1655
	s_add_u32 s14, s22, 0x37c0000
	s_addc_u32 s15, s23, 0
	s_add_i32 s0, s84, s96
	s_lshl_b32 s16, s84, 2
	s_lshl_b32 s17, s96, 2
	s_lshl_b32 s18, s84, 8
	s_lshl_b32 s19, s96, 8
	s_lshl_b32 s24, s0, 19
	s_lshl_b32 s25, s96, 19
	s_mov_b64 s[10:11], 0
	v_mov_b32_e32 v185, 0
	s_mov_b32 s27, 0x40000
	s_mov_b32 s30, 0x80000
	s_mov_b32 s31, 0xc0000
	s_movk_i32 s33, 0x90
	s_mov_b64 s[0:1], 0x40000
	s_mov_b64 s[6:7], 0x80000
	s_add_i32 s34, 16, 0x12000
	s_add_i32 s35, 16, 0x1b000
	s_branch .LBB0_1633
